# workgroups that ran a scan task leave the P3 work queue
# baseline (speedup 1.0000x reference)
; __device__ __forceinline__ void scan_task(const Params& p, int l, int j, LAS unsigned char* lds) {
;     ...
;     float* go = p.out + OFF_GSP + ((size_t)l * 4 + h) * 32768 + dk * 256 + dv;
; #pragma unroll
;     for (int i = 0; i < 4; ++i) go[i * 256] = S[i];
; __global__ void __launch_bounds__(NTHREADS) fwd_megakernel(Params p) {
;     ...
;             for (int n = 0;; ++n) {
;                 int code;
;                 if (sub == 0) {
;                     const int q = queue_next(qc, qslot);
;                     if (q >= 496) break;
;                     code = (q < 64) ? q : (q < 96 ? 608 + (q - 64) : (q < 128 ? 640 + (q - 96) : (q < 160 ? 64 + 512 + (q - 128) : 64 + (q - 160))));
;                 } else {
;                     if (bx < 16) { if (n > 0) break; code = 3000 + bx; }
;                     else {
;                         const int k = bx - 16;
;                         if (k < 64) { if (n < 4) code = 1000 + k + 240 * n; else if (n == 4) code = 1000 + k + 960; else break; }
;                         else { if (n == 0) code = 64 + 336 + (k - 64); else if (n < 5) code = 1000 + k + 240 * (n - 1); else break; }
;                     }
;                 }
;                 if (code < 64) scan_task(p, l, code, lds);
;                 else if (code < 608) gmlp_item(p, l, (code - 64) >> 2, (code - 64) & 3, lds);
;                 else if (code < 640) gla_out_item<true>(p, l, 256 + ((code - 608) >> 2), (code - 608) & 3, lds);
;                 else if (code < 672) gla_sample_state_item(p, l, code - 640, lds);
;                 else if (code < 3000) gla_out_item<false>(p, l, (code - 1000) >> 2, (code - 1000) & 3, lds);
;                 else gemm_phase<1>(lds, p, l, code - 3000);
;             }
.LBB0_591:
	s_ashr_i32 s1, s0, 31
	s_lshl_b64 s[0:1], s[0:1], 19
	v_readlane_b32 s2, v254, 59
	v_ashrrev_i32_e32 v9, 31, v8
	s_add_u32 s0, s2, s0
	v_readlane_b32 s2, v254, 60
	s_addc_u32 s1, s2, s1
	v_lshlrev_b64 v[8:9], 17, v[8:9]
	v_lshl_add_u64 v[8:9], s[0:1], 0, v[8:9]
	v_lshlrev_b32_e32 v0, 10, v82
	v_lshl_add_u64 v[8:9], v[8:9], 0, v[0:1]
	v_lshrrev_b32_e32 v0, 5, v6
	v_and_b32_e32 v0, 0x3fc, v0
	v_lshl_add_u64 v[6:7], v[8:9], 0, v[0:1]
	global_store_dword v[6:7], v2, off
	global_store_dword v[6:7], v3, off offset:1024
	global_store_dword v[6:7], v4, off offset:2048
	global_store_dword v[6:7], v5, off offset:3072
	s_mov_b32 s2, 20
	s_mov_b32 s93, s23
	s_branch .LBB0_593
